# att29 = att20 + prefetched map-0 -> map-1 prologue waits vmcnt(2) (K/Q landed, V0 may still fly; it is only needed after step 0)
# speedup vs baseline: 1.0062x; 1.0062x over previous
.Lqp_wb:
	s_cmp_eq_u32 s100, 2
	s_cbranch_scc1 .Lqp_wb8
	s_waitcnt vmcnt(2) lgkmcnt(0)
	s_branch .Lqp_wb2
